# gemm0a and gemm1: workgroups 256..511 start their tile loop 40 sleep units later so CU partners do not run their k-steps in lockstep
# baseline (speedup 1.0000x reference)
.LBB0_236:
	s_andn2_b64 vcc, exec, s[0:1]
	s_cbranch_vccnz .LBB0_251
	s_cmpk_lt_u32 s88, 0x100
	s_cbranch_scc1 .Lstg_g0a
	s_sleep 40
.Lstg_g0a:
	s_ashr_i32 s24, s88, 3
	s_cmpk_gt_i32 s24, 0xef
	s_cbranch_scc1 .LBB0_251
	v_readlane_b32 s0, v255, 16
	v_readlane_b32 s1, v255, 17
	s_mov_b32 s2, s0
	s_mul_i32 s1, s2, 0x840000
	v_readlane_b32 s4, v254, 62
	v_readlane_b32 s2, v253, 39
	v_readlane_b32 s12, v255, 6
	v_readlane_b32 s3, v253, 40
	s_mul_hi_i32 s0, s0, 0x840000
	v_readlane_b32 s13, v255, 7
	s_add_u32 s42, s12, s1
	s_load_dword s1, s[2:3], 0x0
	v_bfe_u32 v0, v160, 4, 2
	v_lshlrev_b32_e32 v2, 8, v160
	s_addc_u32 s43, s13, s0
	s_and_b32 s0, s88, 7
	v_lshrrev_b32_e32 v188, 1, v0
	v_xor_b32_e32 v0, v0, v188
	v_and_b32_e32 v0, 1, v0
	v_lshl_or_b32 v0, v0, 1, v188
	v_bitop3_b32 v0, v0, v160, 3 bitop3:0x78
	s_waitcnt vmcnt(2)
	v_lshrrev_b32_e32 v5, 2, v160
	v_bfe_u32 v8, v160, 5, 1
	v_and_b32_e32 v2, 0x3c00, v2
	v_ashrrev_i32_e32 v1, 6, v160
	s_xor_b32 s2, s0, 7
	v_bfe_u32 v6, v160, 2, 2
	s_lshl_b32 s45, s0, 4
	v_lshl_or_b32 v2, v0, 3, v2
	v_bitop3_b32 v0, v8, v5, 3 bitop3:0x78
	s_movk_i32 s0, 0x2400
	v_and_b32_e32 v7, 1, v1
	v_lshlrev_b32_e32 v157, 4, v0
	v_bitop3_b32 v0, v8, v6, 2 bitop3:0x36
	v_mul_lo_u32 v5, v1, s0
	v_and_b32_e32 v9, 7, v160
	v_lshlrev_b32_e32 v10, 2, v160
	v_and_b32_e32 v4, 31, v160
	v_lshlrev_b32_e32 v159, 4, v0
	v_lshl_or_b32 v6, v8, 3, v5
	v_lshlrev_b32_e32 v8, 6, v7
	v_lshlrev_b32_e32 v0, 3, v9
	v_bfe_u32 v172, v160, 3, 3
	v_and_b32_e32 v10, 4, v10
	s_movk_i32 s0, 0x1800
	v_lshlrev_b32_e32 v11, 6, v160
	v_lshlrev_b32_e32 v7, 12, v7
	s_waitcnt lgkmcnt(0)
	s_add_i32 s1, s1, s2
	v_lshl_or_b32 v9, v9, 4, v5
	v_and_or_b32 v10, v0, 48, v10
	v_mul_lo_u32 v173, v1, s0
	v_and_b32_e32 v174, 0xffffe7c0, v11
	v_lshlrev_b32_e32 v11, 6, v4
	v_or_b32_e32 v12, v157, v7
	v_or_b32_e32 v7, v159, v7
	v_mul_u32_u24_e32 v4, 0x90, v4
	v_mul_u32_u24_e32 v13, 0x90, v172
	v_lshl_or_b32 v5, v172, 1, v5
	s_movk_i32 s0, 0x90
	s_lshr_b32 s76, s1, 3
	v_and_b32_e32 v161, 0xffffff80, v160
	v_or_b32_e32 v176, 8, v172
	v_or_b32_e32 v178, 16, v172
	v_or_b32_e32 v179, 24, v172
	v_or_b32_e32 v180, 32, v172
	v_or_b32_e32 v181, 40, v172
	v_or_b32_e32 v202, 48, v172
	v_or_b32_e32 v203, 56, v172
	v_mad_u32_u24 v204, v10, s0, v5
	v_or_b32_e32 v205, 0xfffffc00, v8
	v_or_b32_e32 v206, v8, v0
	v_lshlrev_b32_e32 v162, 1, v2
	v_mov_b32_e32 v163, v3
	v_lshlrev_b32_e32 v2, 1, v2
	v_add_u32_e32 v207, v12, v11
	v_add_u32_e32 v208, v7, v11
	v_add_u32_e32 v209, v6, v4
	v_add_u32_e32 v210, v9, v13
	v_readlane_b32 s5, v254, 63
	v_readlane_b32 s6, v255, 0
	v_readlane_b32 s7, v255, 1
	v_readlane_b32 s8, v255, 2
	v_readlane_b32 s9, v255, 3
	v_readlane_b32 s10, v255, 4
	v_readlane_b32 s11, v255, 5
	v_readlane_b32 s14, v255, 8
	v_readlane_b32 s15, v255, 9
	v_readlane_b32 s16, v255, 10
	v_readlane_b32 s17, v255, 11
	v_readlane_b32 s18, v255, 12
	v_readlane_b32 s19, v255, 13
	s_branch .LBB0_240

.LBB0_254:
	s_nop 0
	v_readlane_b32 s0, v255, 19
	v_readlane_b32 s1, v255, 20
	s_and_b64 vcc, exec, s[0:1]
	s_cbranch_vccz .LBB0_261
	s_cmpk_lt_u32 s88, 0x100
	s_cbranch_scc1 .Lstg_g1
	s_sleep 40
.Lstg_g1:
	s_ashr_i32 s24, s88, 3
	s_cmpk_gt_i32 s24, 0x7f
	s_cbranch_scc1 .LBB0_260
	v_readlane_b32 s0, v255, 16
	v_readlane_b32 s1, v255, 17
	s_mov_b32 s2, s0
	s_ashr_i32 s3, s0, 31
	v_writelane_b32 v255, s0, 16
	v_readlane_b32 s4, v254, 62
	s_waitcnt vmcnt(2)
	v_bfe_u32 v4, v160, 4, 2
	v_writelane_b32 v255, s1, 17
	s_lshl_b64 s[0:1], s[2:3], 21
	v_readlane_b32 s2, v253, 39
	v_readlane_b32 s14, v255, 8
	v_readlane_b32 s3, v253, 40
	s_add_u32 s46, s14, s0
	s_load_dword s0, s[2:3], 0x0
	v_readlane_b32 s15, v255, 9
	s_addc_u32 s47, s15, s1
	s_and_b32 s1, s88, 7
	s_xor_b32 s2, s1, 7
	v_lshlrev_b32_e32 v2, 8, v160
	s_waitcnt lgkmcnt(0)
	s_add_i32 s0, s0, s2
	v_lshrrev_b32_e32 v188, 1, v4
	v_xor_b32_e32 v189, v4, v188
	v_and_b32_e32 v189, 1, v189
	v_lshl_or_b32 v189, v189, 1, v188
	v_bitop3_b32 v0, v189, v160, 3 bitop3:0x78
	v_lshrrev_b32_e32 v5, 2, v160
	v_bfe_u32 v8, v160, 5, 1
	v_and_b32_e32 v2, 0x3c00, v2
	s_lshr_b32 s48, s0, 3
	v_bfe_u32 v6, v160, 2, 2
	s_lshl_b32 s49, s1, 4
	v_lshl_or_b32 v2, v0, 3, v2
	v_bitop3_b32 v0, v8, v5, 3 bitop3:0x78
	v_readlane_b32 s0, v253, 3
	v_lshlrev_b32_e32 v157, 4, v0
	v_bitop3_b32 v0, v8, v6, 2 bitop3:0x36
	s_add_i32 s0, s0, 5
	v_ashrrev_i32_e32 v1, 6, v160
	v_lshlrev_b32_e32 v159, 4, v0
	s_cmp_lt_u32 s0, 13
	s_movk_i32 s0, 0x2200
	v_lshlrev_b32_e32 v0, 2, v160
	v_and_b32_e32 v7, 1, v1
	v_and_b32_e32 v9, 31, v160
	v_mul_lo_u32 v5, v1, s0
	v_and_b32_e32 v6, 60, v0
	s_movk_i32 s0, 0x110
	v_lshl_or_b32 v0, v7, 6, v6
	v_mad_u32_u24 v10, v9, s0, v5
	v_lshl_or_b32 v5, v6, 2, v5
	v_lshlrev_b32_e32 v6, 6, v160
	v_and_b32_e32 v173, 0xffffe7c0, v6
	v_lshlrev_b32_e32 v6, 12, v7
	v_readlane_b32 s60, v253, 7
	v_readlane_b32 s10, v255, 4
	v_readlane_b32 s11, v255, 5
	v_readlane_b32 s1, v253, 4
	v_and_or_b32 v161, v160, s52, v4
	v_lshlrev_b32_e32 v8, 4, v8
	s_movk_i32 s0, 0x1800
	v_lshlrev_b32_e32 v7, 6, v9
	v_or_b32_e32 v9, v157, v6
	v_or_b32_e32 v6, v159, v6
	v_mul_u32_u24_e32 v4, 0x110, v4
	v_readlane_b32 s61, v253, 8
	v_mul_lo_u32 v172, v1, s0
	s_cselect_b32 s1, s61, s11
	s_cselect_b32 s0, s60, s10
	v_lshlrev_b32_e32 v162, 1, v2
	v_mov_b32_e32 v163, v3
	v_lshlrev_b32_e32 v2, 1, v2
	v_add_u32_e32 v174, v10, v8
	v_add_u32_e32 v176, v5, v4
	v_add_u32_e32 v178, v9, v7
	v_add_u32_e32 v179, v6, v7
	v_readlane_b32 s5, v254, 63
	v_readlane_b32 s6, v255, 0
	v_readlane_b32 s7, v255, 1
	v_readlane_b32 s8, v255, 2
	v_readlane_b32 s9, v255, 3
	v_readlane_b32 s12, v255, 6
	v_readlane_b32 s13, v255, 7
	v_readlane_b32 s16, v255, 10
	v_readlane_b32 s17, v255, 11
	v_readlane_b32 s18, v255, 12
	v_readlane_b32 s19, v255, 13
	v_readlane_b32 s2, v253, 5
	v_readlane_b32 s3, v253, 6
	v_readlane_b32 s62, v253, 9
	v_readlane_b32 s63, v253, 10
	v_readlane_b32 s64, v253, 11
	v_readlane_b32 s65, v253, 12
	v_readlane_b32 s66, v253, 13
	v_readlane_b32 s67, v253, 14
	v_readlane_b32 s68, v253, 15
	v_readlane_b32 s69, v253, 16
	v_readlane_b32 s70, v253, 17
	v_readlane_b32 s71, v253, 18
	v_readlane_b32 s72, v253, 19
	v_readlane_b32 s73, v253, 20
	v_readlane_b32 s74, v253, 21
	v_readlane_b32 s75, v253, 22
